# grid barrier between W_down[0] quantisation and in-projection GEMM removed (independent phases), on top of v15 (K-loop prio-before-barrier, merged waits, P0 item pipeline)
# speedup vs baseline: 1.0054x; 1.0054x over previous
.LBB0_379:
	s_or_b64 exec, exec, s[10:11]
	s_mov_b32 s41, s92
	s_mov_b64 s[0:1], s[94:95]
	s_waitcnt lgkmcnt(0)
	v_mov_b32_e32 v1, v0
	s_load_dwordx2 s[18:19], s[0:1], 0xc8
	v_readlane_b32 s7, v252, 2
	s_cmpk_lt_i32 s7, 0x400
	s_cselect_b64 s[0:1], -1, 0
	v_mov_b32_e32 v10, v0
	v_readfirstlane_b32 s23, v1
	s_and_b64 vcc, exec, s[0:1]
	v_readfirstlane_b32 s8, v10
	s_cbranch_vccz .LBB0_433
	s_ashr_i32 s2, s7, 31
	s_lshr_b32 s2, s2, 29
	s_add_i32 s2, s7, s2
	s_and_b32 s3, s2, -8
	s_sub_i32 s3, s7, s3
	s_lshl_b32 s5, s3, 7
	s_ashr_i32 s2, s2, 3
	s_mul_i32 s4, s3, 0x81
	s_cmp_lt_i32 s3, 0
	s_cselect_b32 s3, s4, s5
	s_add_i32 s2, s3, s2
	s_ashr_i32 s3, s2, 31
	s_lshr_b32 s3, s3, 24
	s_add_i32 s3, s2, s3
	s_ashr_i32 s4, s3, 8
	s_and_b32 s3, s3, 0xffffff00
	s_sub_i32 s2, s2, s3
	s_sext_i32_i16 s3, s2
	s_bfe_u32 s3, s3, 0x3001c
	s_add_i32 s3, s2, s3
	s_sext_i32_i16 s5, s3
	s_and_b32 s3, s3, 0xfff8
	s_sub_i32 s2, s2, s3
	s_lshl_b32 s4, s4, 3
	s_sext_i32_i16 s2, s2
	s_add_i32 s2, s4, s2
	s_ashr_i32 s6, s5, 3
